# drops the h3-before-attention reordering (no measurable effect): attention body, P0 rebalance, early acquire invalidate, P3 P4 merge
# baseline (speedup 1.0000x reference)
; #define PHASE(k, ...) if (IN(k)) { { __VA_ARGS__ } if (DUPON(k)) { __VA_ARGS__ } SEAM(k); }
; __global__ void __launch_bounds__(NTHR) mk_fwd(Args a) {
;     ...
;     PHASE(7,  const bf16_t* Q = WSB(SL(3)); const bf16_t* K = (const bf16_t*)((unsigned char*)a.out + 64 * MiB); const bf16_t* Vt = WSB(SL(8)); bf16_t* O = (bf16_t*)a.out;
;                  float mfix; { const int ln = threadIdx.x & 63; float gqm = fmaxf(fabsf(a.in[11][ln]), fabsf(a.in[11][64 + (ln & 31)])), gkm = fmaxf(fabsf(a.in[12][ln]), fabsf(a.in[12][64 + (ln & 31)]));
;                      for (int o = 1; o < 64; o <<= 1) { gqm = fmaxf(gqm, __shfl_xor(gqm, o)); gkm = fmaxf(gkm, __shfl_xor(gkm, o)); }
;                      mfix = 14.135f * 1.02f * gqm * gkm; }
;                  const bool fix = mfix <= 40.f;
.LBB0_704:
	s_cmp_lt_i32 s84, 8
	s_cselect_b64 s[0:1], -1, 0
	s_cmp_gt_i32 s85, 7
	s_cselect_b64 s[4:5], -1, 0
	s_and_b64 s[0:1], s[0:1], s[4:5]
	s_andn2_b64 vcc, exec, s[0:1]
	s_cbranch_vccnz .LBB0_893
	v_and_b32_e32 v195, 31, v254
	s_waitcnt vmcnt(0)
	v_and_b32_e32 v0, 63, v254
	s_waitcnt lgkmcnt(0)
	v_lshlrev_b32_e32 v1, 2, v195
	v_lshlrev_b32_e32 v0, 2, v0
	global_load_dword v2, v1, s[74:75] offset:256
	global_load_dword v3, v0, s[74:75]
	global_load_dword v4, v1, s[76:77] offset:256
	global_load_dword v5, v0, s[76:77]
	v_mbcnt_lo_u32_b32 v0, -1, 0
	v_lshlrev_b32_e32 v16, 3, v254
	v_mbcnt_hi_u32_b32 v0, -1, v0
	v_and_b32_e32 v10, 56, v16
	v_and_b32_e32 v201, 64, v0
	v_add_u32_e32 v6, 0x200, v254
	v_xor_b32_e32 v17, 1, v0
	v_lshlrev_b32_e32 v158, 1, v10
	v_add_u32_e32 v10, 64, v201
	v_mul_u32_u24_e32 v8, 0x1556, v254
	v_mov_b32_e32 v9, 12
	s_mov_b32 s4, 0x7060302
	v_mul_u32_u24_e32 v12, 0x1556, v6
	v_cmp_lt_i32_e32 vcc, v17, v10
	v_mul_lo_u16_sdwa v11, v8, v9 dst_sel:DWORD dst_unused:UNUSED_PAD src0_sel:WORD_1 src1_sel:DWORD
	v_perm_b32 v8, v12, v8, s4
	v_mul_lo_u16_sdwa v9, v12, v9 dst_sel:DWORD dst_unused:UNUSED_PAD src0_sel:WORD_1 src1_sel:DWORD
	v_cndmask_b32_e32 v12, v0, v17, vcc
	v_lshlrev_b32_e32 v12, 2, v12
	v_lshrrev_b32_e32 v7, 3, v254
	v_xor_b32_e32 v18, 2, v0
	v_bfe_u32 v1, v254, 5, 1
	s_movk_i32 s6, 0xd0
	v_mul_u32_u24_e32 v13, 0x88, v7
	v_xor_b32_e32 v19, 4, v0
	v_cmp_lt_i32_e32 vcc, v18, v10
	v_lshlrev_b32_e32 v199, 3, v1
	v_mad_u32_u24 v14, v195, s6, 0
	v_lshlrev_b32_e32 v156, 4, v1
	v_mul_i32_i24_e32 v15, 0xffffffb8, v195
	v_xor_b32_e32 v20, 8, v0
	v_add3_u32 v189, 0, v13, v158
	v_cndmask_b32_e32 v13, v0, v18, vcc
	v_cmp_lt_i32_e32 vcc, v19, v10
	v_xor_b32_e32 v21, 16, v0
	v_add_u32_e32 v188, v14, v156
	v_add3_u32 v198, v14, v15, v199
	v_cndmask_b32_e32 v14, v0, v19, vcc
	v_cmp_lt_i32_e32 vcc, v20, v10
	v_xor_b32_e32 v22, 32, v0
	v_sub_u16_e32 v9, v6, v9
	v_cndmask_b32_e32 v15, v0, v20, vcc
	v_cmp_lt_i32_e32 vcc, v21, v10
	v_lshlrev_b32_e32 v190, 4, v9
	v_lshlrev_b32_e32 v9, 2, v15
	v_cndmask_b32_e32 v17, v0, v21, vcc
	v_cmp_lt_i32_e32 vcc, v22, v10
	v_lshlrev_b32_e32 v10, 2, v13
	v_lshlrev_b32_e32 v186, 2, v17
	v_cndmask_b32_e32 v0, v0, v22, vcc
	v_lshlrev_b32_e32 v187, 2, v0
	s_add_u32 s49, s50, 0x4000000
	s_addc_u32 s54, s51, 0
	s_add_u32 s55, s30, 0x6000000
	s_addc_u32 s56, s31, 0
	s_add_u32 s59, s30, 0x10000000
	s_addc_u32 s60, s31, 0
	s_cmpk_lg_i32 s86, 0x100
	s_cbranch_scc1 .Lvt_cd
	s_bitcmp1_b32 s2, 4
	s_cbranch_scc1 .Lvt_c1
	s_add_u32 s59, s50, 0x7000000
	s_addc_u32 s60, s51, 0
	s_branch .Lvt_cd

; #define LAS __attribute__((address_space(3)))
; __device__ __forceinline__ void attn_unit64(const bf16_t* Q, const bf16_t* K, const bf16_t* Vt, bf16_t* O, int bh, int qb8, float mfix, LAS unsigned char* lds) {
;     const int tid = threadIdx.x, lane = tid & 63, wid = __builtin_amdgcn_readfirstlane(tid >> 6), r = lane & 31, hh = lane >> 5;
;     LAS bf16_t* Kb = (LAS bf16_t*)lds;
;     LAS bf16_t* Vb = (LAS bf16_t*)(lds + 2 * 64 * 104 * 2);
;     const bf16_t* Qh = Q + (size_t)bh * SEQ * 96; const bf16_t* Kh = K + (size_t)bh * SEQ * 96; const bf16_t* Vh = Vt + (size_t)(bh & 7) * 64 * T + (size_t)(bh >> 3) * SEQ;
;     const int q0 = qb8 * 512, qw = q0 + wid * 64, NTL = 8 * (qb8 + 1), tmaxw = 8 * qb8 + wid;
;     LAS bf16x8* Qs = (LAS bf16x8*)(lds + 2 * 64 * 104 * 2 + 2 * 64 * 68 * 2) + tid;
; #pragma unroll
;     for (int d0 = 0; d0 < 6; ++d0) { Qs[512 * d0] = __builtin_nontemporal_load((const bf16x8*)(Qh + (size_t)(qw + r) * 96 + 16 * d0 + 8 * hh)); Qs[512 * (6 + d0)] = __builtin_nontemporal_load((const bf16x8*)(Qh + (size_t)(qw + 32 + r) * 96 + 16 * d0 + 8 * hh)); }
;     f32x16 oA0, oA1, oB0, oB1;
; #pragma unroll
;     for (int i = 0; i < 16; ++i) { oA0[i] = 0.f; oA1[i] = 0.f; oB0[i] = 0.f; oB1[i] = 0.f; }
;     float lA = 0.f, lB = 0.f;
;     const int c2 = 512 + tid, kr1 = tid / 12, kc1 = tid % 12, kr2 = c2 / 12, kc2 = c2 % 12, vr = tid >> 3, vc = tid & 7;
;     u32x4 kA, kB = {0u, 0u, 0u, 0u}, vA;
; __global__ void __launch_bounds__(NTHR) mk_fwd(Args a) {
;     ...
;                  float mfix; { const int ln = threadIdx.x & 63; float gqm = fmaxf(fabsf(a.in[11][ln]), fabsf(a.in[11][64 + (ln & 31)])), gkm = fmaxf(fabsf(a.in[12][ln]), fabsf(a.in[12][64 + (ln & 31)]));
;                      for (int o = 1; o < 64; o <<= 1) { gqm = fmaxf(gqm, __shfl_xor(gqm, o)); gkm = fmaxf(gkm, __shfl_xor(gkm, o)); }
;                      mfix = 14.135f * 1.02f * gqm * gkm; }
;                  const bool fix = mfix <= 40.f;
;                  for (int rep = 0; rep < (DUPON(19) ? 2 : 1); ++rep) {
;                  if (fix) { if (G == 256) { const int bh = bid >> 2, s = bid & 3; attn_unit64(Q, K, Vt, O, bh, 7 - s, mfix, lds); attn_unit64(Q, K, Vt, O, bh, s, mfix, lds); }
;                             else { for (int j = bid; j < 512; j += G) attn_unit64(Q, K, Vt, O, j >> 3, 7 - (j & 7), mfix, lds); } }
.Lvt_cd:
	s_mov_b32 s3, 0x42200000
	s_cmpk_lt_i32 s2, 0x200
	s_cselect_b64 s[6:7], -1, 0
	s_and_b32 s42, s2, 3
	s_xor_b32 s43, s42, 7
	s_mov_b32 s5, 0xd00068
	v_pk_mul_lo_u16 v8, v8, s5
	v_mov_b32_e32 v157, 0
	v_sub_u16_e32 v11, v254, v11
	v_lshlrev_b16_e32 v11, 3, v11
	s_movk_i32 s0, 0x100
	v_lshlrev_b32_e32 v192, 1, v11
	v_lshrrev_b32_e32 v191, 16, v8
	v_mov_b32_e32 v159, v157
	v_cmp_gt_u32_e64 s[0:1], s0, v254
	v_lshlrev_b32_e32 v206, 3, v6
	v_lshlrev_b32_e32 v207, 15, v7
	v_add_u32_e32 v196, 0, v191
	v_lshlrev_b32_e32 v194, 2, v1
	s_waitcnt vmcnt(3)
	v_max_f32_e64 v2, |v2|, |v2|
	s_waitcnt vmcnt(2)
	v_max_f32_e64 v3, |v3|, |v3|
	s_waitcnt vmcnt(1)
	v_max_f32_e64 v4, |v4|, |v4|
	s_waitcnt vmcnt(0)
	v_max_f32_e64 v5, |v5|, |v5|
	v_max_f32_e32 v2, v3, v2
	v_max_f32_e32 v3, v5, v4
	ds_bpermute_b32 v4, v12, v2
	ds_bpermute_b32 v5, v12, v3
	v_lshlrev_b32_e32 v12, 2, v14
	s_waitcnt lgkmcnt(1)
	v_max_f32_e32 v4, v4, v4
	s_waitcnt lgkmcnt(0)
	v_max_f32_e32 v5, v5, v5
	v_max_f32_e32 v2, v2, v4
	v_max_f32_e32 v3, v3, v5
	ds_bpermute_b32 v4, v10, v2
	ds_bpermute_b32 v5, v10, v3
	v_and_b32_e32 v10, 0xfff8, v8
	v_lshlrev_b32_e32 v193, 1, v10
	v_add3_u32 v197, 0, v193, v192
	s_waitcnt lgkmcnt(1)
	v_max_f32_e32 v4, v4, v4
	s_waitcnt lgkmcnt(0)
	v_max_f32_e32 v5, v5, v5
	v_max_f32_e32 v2, v2, v4
	v_max_f32_e32 v3, v3, v5
	ds_bpermute_b32 v4, v12, v2
	ds_bpermute_b32 v5, v12, v3
	s_waitcnt lgkmcnt(1)
	v_max_f32_e32 v4, v4, v4
	s_waitcnt lgkmcnt(0)
	v_max_f32_e32 v5, v5, v5
	v_max_f32_e32 v2, v2, v4
	v_max_f32_e32 v3, v3, v5
	ds_bpermute_b32 v4, v9, v2
	ds_bpermute_b32 v5, v9, v3
	s_waitcnt lgkmcnt(1)
	v_max_f32_e32 v0, v4, v4
	s_waitcnt lgkmcnt(0)
	v_max_f32_e32 v4, v5, v5
	v_max_f32_e32 v0, v2, v0
	v_max_f32_e32 v2, v3, v4
	ds_bpermute_b32 v3, v186, v0
	ds_bpermute_b32 v4, v186, v2
	s_waitcnt lgkmcnt(1)
	v_max_f32_e32 v3, v3, v3
	s_waitcnt lgkmcnt(0)
	v_max_f32_e32 v4, v4, v4
	v_max_f32_e32 v0, v0, v3
	v_max_f32_e32 v2, v2, v4
	ds_bpermute_b32 v3, v187, v0
	ds_bpermute_b32 v4, v187, v2
	s_waitcnt lgkmcnt(1)
	v_max_f32_e32 v3, v3, v3
	s_waitcnt lgkmcnt(0)
	v_max_f32_e32 v4, v4, v4
	v_max_f32_e32 v0, v0, v3
	v_max_f32_e32 v2, v2, v4
	v_mul_f32_e32 v0, 0x4166aee6, v0
	v_mul_f32_e32 v0, v2, v0
	v_cmp_ge_f32_e32 vcc, s3, v0
	s_ashr_i32 s3, s2, 2
	s_mul_i32 s58, s3, 0xc0000
	s_mul_hi_i32 s57, s3, 0xc0000
	s_add_u32 s4, s55, s58
	s_addc_u32 s5, s56, s57
	s_ashr_i32 s10, s2, 5
	s_and_b32 s3, s3, 7
	s_ashr_i32 s11, s10, 31
	s_lshl_b64 s[8:9], s[10:11], 13
	v_lshl_add_u64 v[154:155], s[4:5], 0, v[156:157]
	s_lshl_b32 s4, s3, 22
	s_add_u32 s4, s59, s4
	s_addc_u32 s5, s60, 0
	s_add_u32 s4, s4, s8
	s_addc_u32 s5, s5, s9
	s_add_u32 s12, s49, s58
	s_addc_u32 s13, s54, s57
	s_lshl_b32 s48, s10, 12
	s_lshl_b32 s3, s3, 7
	v_lshlrev_b32_e32 v2, 4, v6
	v_mov_b32_e32 v3, v157
	s_add_u32 s10, s50, s3
	v_lshl_add_u64 v[148:149], s[12:13], 0, v[2:3]
	v_lshlrev_b32_e32 v2, 16, v7
	s_addc_u32 s11, s51, 0
	v_lshlrev_b32_e32 v156, 4, v254
	v_lshl_add_u64 v[2:3], s[4:5], 0, v[2:3]
	s_cmpk_lg_i32 s86, 0x100
	v_lshl_add_u64 v[152:153], s[12:13], 0, v[156:157]
	v_lshl_add_u64 v[150:151], v[2:3], 0, v[158:159]
	s_cselect_b64 s[12:13], -1, 0
	s_mov_b64 s[4:5], 0
	s_and_saveexec_b64 s[14:15], vcc
	s_xor_b64 s[14:15], exec, s[14:15]
	s_cbranch_execz .LBB0_731
	v_lshl_add_u32 v200, v254, 4, 0
	v_xor_b32_e32 v0, 0x80000000, v0
	v_add_u32_e32 v201, 0xac00, v200
	v_add_u32_e32 v202, 0x1ac00, v200
	v_add_u32_e32 v203, 0x1cc00, v200
	v_add_u32_e32 v204, 0x1ec00, v200
	v_add_u32_e32 v205, 0x20c00, v200
	v_mov_b32_e32 v1, v0
	v_mov_b32_e32 v2, v0
	v_mov_b32_e32 v3, v0
	v_mov_b32_e32 v4, v0
	v_mov_b32_e32 v5, v0
	v_mov_b32_e32 v6, v0
	v_mov_b32_e32 v7, v0
	v_mov_b32_e32 v8, v0
	v_mov_b32_e32 v9, v0
	v_mov_b32_e32 v10, v0
	v_mov_b32_e32 v11, v0
	v_mov_b32_e32 v12, v0
	v_mov_b32_e32 v13, v0
	v_mov_b32_e32 v14, v0
	v_mov_b32_e32 v15, v0
	s_and_b64 vcc, exec, s[12:13]
	s_cbranch_vccz .LBB0_786
	s_mov_b64 s[16:17], 0
	s_and_b64 vcc, exec, s[6:7]
	s_cbranch_vccz .LBB0_787
	v_mov_b32_e32 v112, 0
	v_mov_b32_e32 v157, v112
	v_lshl_add_u64 v[18:19], s[50:51], 0, v[156:157]
	s_mov_b64 s[4:5], 0x4003000
	v_lshl_add_u64 v[128:129], v[18:19], 0, s[4:5]
	v_and_b32_e32 v18, 7, v254
	v_lshlrev_b32_e32 v17, 13, v254
	v_lshlrev_b32_e32 v18, 4, v18
	s_mov_b32 s4, 0x7f0000
	v_and_or_b32 v18, v17, s4, v18
	v_mov_b32_e32 v19, v112
	v_lshl_add_u64 v[18:19], s[30:31], 0, v[18:19]
	s_mov_b64 s[4:5], 0x10000080
	v_lshlrev_b32_e32 v132, 1, v199
	s_xor_b32 s3, s2, 7
	v_lshl_add_u64 v[130:131], v[18:19], 0, s[4:5]
	s_movk_i32 s28, 0xc0
	v_mov_b32_e32 v134, v132
	v_mov_b32_e32 v135, v112
	v_lshlrev_b32_e32 v157, 1, v16
	s_mov_b32 s19, 0
	v_lshlrev_b32_e32 v136, 1, v207
	v_mov_b32_e32 v137, v112
	v_mov_b32_e32 v159, v112
	v_add_u32_e32 v207, v196, v190
	v_add_u32_e32 v208, 0x6800, v189
	v_mov_b32_e32 v209, 0xc0000
	s_mov_b64 s[20:21], 0x3000
	s_mov_b64 s[22:23], 0x80
	s_mov_b64 s[24:25], 0x10000
	s_mov_b32 s29, 0x10000
	v_lshlrev_b32_e32 v206, 1, v206
	v_mov_b32_e32 v210, 0xf149f2ca
	s_mov_b32 s61, s2
	s_branch .LBB0_710
